# each workgroup writes back its XCD L2 (buffer_wbl2 sc1) when it arrives at a seam, before the arrival atomic, so the XCD leader's release writeback is short
# baseline (speedup 1.0000x reference)
.LBB0_143:
	s_cmp_gt_i32 s31, 1
	s_cselect_b64 s[0:1], -1, 0
	s_and_b64 s[4:5], s[74:75], s[0:1]
	s_andn2_b64 vcc, exec, s[4:5]
	s_cbranch_vccnz .LBB0_197
	s_waitcnt vmcnt(0)
	s_waitcnt lgkmcnt(0)
	s_barrier
	s_mov_b64 s[4:5], exec
	v_readlane_b32 s6, v254, 1
	v_readlane_b32 s7, v254, 2
	s_and_b64 s[6:7], s[4:5], s[6:7]
	s_mov_b64 exec, s[6:7]
	s_cbranch_execz .LBB0_196
	buffer_wbl2 sc1
	s_add_i32 s3, 0, 0x23ff0
	v_mov_b32_e32 v0, s3
	s_waitcnt vmcnt(0) expcnt(0) lgkmcnt(0)
	ds_read_b32 v2, v0
	s_add_i32 s3, 0, 0x23ff4
	v_mov_b32_e32 v0, s3
	ds_read_b32 v0, v0
	s_waitcnt lgkmcnt(1)
	v_cmp_ne_u32_e32 vcc, 0, v2
	s_cbranch_vccnz .LBB0_160
	s_add_u32 s6, s28, 0x40200
	s_addc_u32 s7, s29, 0
	s_add_u32 s8, s28, 0x40400
	s_addc_u32 s9, s29, 0
	s_add_u32 s12, s28, 0x40500
	s_addc_u32 s13, s29, 0
	s_add_u32 s14, s28, 0x40600
	s_addc_u32 s15, s29, 0
	s_add_u32 s16, s28, 0x40700
	s_addc_u32 s17, s29, 0
	s_add_u32 s20, s28, 0x40800
	s_addc_u32 s21, s29, 0
	s_add_u32 s22, s28, 0x40900
	s_addc_u32 s23, s29, 0
	s_add_u32 s26, s28, 0x40a00
	s_addc_u32 s27, s29, 0
	s_add_u32 s38, s28, 0x40b00
	s_addc_u32 s39, s29, 0
	s_add_u32 s40, s28, 0x40c00
	s_addc_u32 s41, s29, 0
	s_add_u32 s42, s28, 0x40d00
	s_addc_u32 s43, s29, 0
	s_add_u32 s44, s28, 0x40e00
	s_addc_u32 s45, s29, 0
	s_add_u32 s46, s28, 0x40f00
	s_addc_u32 s47, s29, 0
	s_add_u32 s48, s28, 0x41000
	s_addc_u32 s49, s29, 0
	s_add_u32 s50, s28, 0x41100
	s_addc_u32 s51, s29, 0
	s_add_u32 s52, s28, 0x41200
	v_readlane_b32 s3, v254, 0
	s_addc_u32 s53, s29, 0
	s_mul_i32 s3, s35, s3
	s_add_u32 s54, s28, 0x41300
	s_mul_i32 s3, s3, s34
	s_addc_u32 s55, s29, 0
	s_mov_b32 s10, 1
	v_mov_b32_e32 v16, 0
	s_branch .LBB0_148

.LBB0_266:
	s_cmp_gt_i32 s31, 2
	s_cselect_b64 s[4:5], -1, 0
	s_and_b64 s[0:1], s[0:1], s[4:5]
	s_andn2_b64 vcc, exec, s[0:1]
	s_cbranch_vccnz .LBB0_320
	s_waitcnt vmcnt(0)
	s_waitcnt vmcnt(0) lgkmcnt(0)
	s_barrier
	s_mov_b64 s[0:1], exec
	v_readlane_b32 s6, v254, 1
	v_readlane_b32 s7, v254, 2
	s_and_b64 s[6:7], s[0:1], s[6:7]
	s_mov_b64 exec, s[6:7]
	s_cbranch_execz .LBB0_319
	buffer_wbl2 sc1
	s_add_i32 s3, 0, 0x23ff0
	v_mov_b32_e32 v0, s3
	s_waitcnt vmcnt(0) expcnt(0) lgkmcnt(0)
	ds_read_b32 v2, v0
	s_add_i32 s3, 0, 0x23ff4
	v_mov_b32_e32 v0, s3
	ds_read_b32 v0, v0
	s_waitcnt lgkmcnt(1)
	v_cmp_ne_u32_e32 vcc, 0, v2
	s_cbranch_vccnz .LBB0_283
	s_add_u32 s6, s28, 0x40200
	s_addc_u32 s7, s29, 0
	s_add_u32 s8, s28, 0x40400
	s_addc_u32 s9, s29, 0
	s_add_u32 s16, s28, 0x40500
	s_addc_u32 s17, s29, 0
	s_add_u32 s26, s28, 0x40600
	s_addc_u32 s27, s29, 0
	s_add_u32 s38, s28, 0x40700
	s_addc_u32 s39, s29, 0
	s_add_u32 s40, s28, 0x40800
	s_addc_u32 s41, s29, 0
	s_add_u32 s42, s28, 0x40900
	s_addc_u32 s43, s29, 0
	s_add_u32 s44, s28, 0x40a00
	s_addc_u32 s45, s29, 0
	s_add_u32 s46, s28, 0x40b00
	s_addc_u32 s47, s29, 0
	s_add_u32 s48, s28, 0x40c00
	s_addc_u32 s49, s29, 0
	s_add_u32 s50, s28, 0x40d00
	s_addc_u32 s51, s29, 0
	s_add_u32 s52, s28, 0x40e00
	s_addc_u32 s53, s29, 0
	s_add_u32 s54, s28, 0x40f00
	s_addc_u32 s55, s29, 0
	s_add_u32 s72, s28, 0x41000
	s_addc_u32 s73, s29, 0
	s_add_u32 s74, s28, 0x41100
	s_addc_u32 s75, s29, 0
	s_add_u32 s76, s28, 0x41200
	v_readlane_b32 s3, v254, 0
	s_addc_u32 s77, s29, 0
	s_mul_i32 s3, s35, s3
	s_add_u32 s78, s28, 0x41300
	s_mul_i32 s3, s3, s34
	s_addc_u32 s79, s29, 0
	s_mov_b32 s10, 1
	v_mov_b32_e32 v16, 0
	s_branch .LBB0_271

.LBB0_398:
	s_cmp_gt_i32 s31, 3
	s_cselect_b64 s[0:1], -1, 0
	s_and_b64 s[4:5], s[16:17], s[0:1]
	s_andn2_b64 vcc, exec, s[4:5]
	s_cbranch_vccnz .LBB0_452
	s_waitcnt vmcnt(0)
	s_waitcnt vmcnt(0) lgkmcnt(0)
	s_barrier
	s_mov_b64 s[4:5], exec
	v_readlane_b32 s6, v254, 1
	v_readlane_b32 s7, v254, 2
	s_and_b64 s[6:7], s[4:5], s[6:7]
	s_mov_b64 exec, s[6:7]
	s_cbranch_execz .LBB0_451
	buffer_wbl2 sc1
	s_add_i32 s3, 0, 0x23ff0
	v_mov_b32_e32 v0, s3
	s_waitcnt vmcnt(0) expcnt(0) lgkmcnt(0)
	ds_read_b32 v2, v0
	s_add_i32 s3, 0, 0x23ff4
	v_mov_b32_e32 v0, s3
	ds_read_b32 v0, v0
	s_waitcnt lgkmcnt(1)
	v_cmp_ne_u32_e32 vcc, 0, v2
	s_cbranch_vccnz .LBB0_415
	s_add_u32 s6, s28, 0x40200
	s_addc_u32 s7, s29, 0
	s_add_u32 s8, s28, 0x40400
	s_addc_u32 s9, s29, 0
	s_add_u32 s12, s28, 0x40500
	s_addc_u32 s13, s29, 0
	s_add_u32 s14, s28, 0x40600
	s_addc_u32 s15, s29, 0
	s_add_u32 s16, s28, 0x40700
	s_addc_u32 s17, s29, 0
	s_add_u32 s26, s28, 0x40800
	s_addc_u32 s27, s29, 0
	s_add_u32 s44, s28, 0x40900
	s_addc_u32 s45, s29, 0
	s_add_u32 s46, s28, 0x40a00
	s_addc_u32 s47, s29, 0
	s_add_u32 s48, s28, 0x40b00
	s_addc_u32 s49, s29, 0
	s_add_u32 s50, s28, 0x40c00
	s_addc_u32 s51, s29, 0
	s_add_u32 s52, s28, 0x40d00
	s_addc_u32 s53, s29, 0
	s_add_u32 s54, s28, 0x40e00
	s_addc_u32 s55, s29, 0
	s_add_u32 s68, s28, 0x40f00
	s_addc_u32 s69, s29, 0
	s_add_u32 s70, s28, 0x41000
	s_addc_u32 s71, s29, 0
	s_add_u32 s72, s28, 0x41100
	s_addc_u32 s73, s29, 0
	s_add_u32 s74, s28, 0x41200
	v_readlane_b32 s3, v254, 0
	s_addc_u32 s75, s29, 0
	s_mul_i32 s3, s35, s3
	s_add_u32 s76, s28, 0x41300
	s_mul_i32 s3, s3, s34
	s_addc_u32 s77, s29, 0
	s_mov_b32 s10, 1
	v_mov_b32_e32 v16, 0
	s_branch .LBB0_403

.LBB0_492:
	s_cmp_gt_i32 s31, 4
	s_cselect_b64 s[0:1], -1, 0
	s_and_b64 s[4:5], s[44:45], s[0:1]
	s_andn2_b64 vcc, exec, s[4:5]
	s_cbranch_vccnz .LBB0_546
	s_waitcnt vmcnt(0)
	s_waitcnt vmcnt(0) lgkmcnt(0)
	s_barrier
	s_mov_b64 s[4:5], exec
	v_readlane_b32 s6, v254, 1
	v_readlane_b32 s7, v254, 2
	s_and_b64 s[6:7], s[4:5], s[6:7]
	s_mov_b64 exec, s[6:7]
	s_cbranch_execz .LBB0_545
	buffer_wbl2 sc1
	s_add_i32 s3, 0, 0x23ff0
	v_mov_b32_e32 v0, s3
	s_waitcnt vmcnt(0) expcnt(0) lgkmcnt(0)
	ds_read_b32 v2, v0
	s_add_i32 s3, 0, 0x23ff4
	v_mov_b32_e32 v0, s3
	ds_read_b32 v0, v0
	s_waitcnt lgkmcnt(1)
	v_cmp_ne_u32_e32 vcc, 0, v2
	s_cbranch_vccnz .LBB0_509
	s_add_u32 s6, s28, 0x40200
	s_addc_u32 s7, s29, 0
	s_add_u32 s8, s28, 0x40400
	s_addc_u32 s9, s29, 0
	s_add_u32 s12, s28, 0x40500
	s_addc_u32 s13, s29, 0
	s_add_u32 s14, s28, 0x40600
	s_addc_u32 s15, s29, 0
	s_add_u32 s16, s28, 0x40700
	s_addc_u32 s17, s29, 0
	s_add_u32 s18, s28, 0x40800
	s_addc_u32 s19, s29, 0
	s_add_u32 s38, s28, 0x40900
	s_addc_u32 s39, s29, 0
	s_add_u32 s40, s28, 0x40a00
	s_addc_u32 s41, s29, 0
	s_add_u32 s42, s28, 0x40b00
	s_addc_u32 s43, s29, 0
	s_add_u32 s44, s28, 0x40c00
	s_addc_u32 s45, s29, 0
	s_add_u32 s46, s28, 0x40d00
	s_addc_u32 s47, s29, 0
	s_add_u32 s48, s28, 0x40e00
	s_addc_u32 s49, s29, 0
	s_add_u32 s50, s28, 0x40f00
	s_addc_u32 s51, s29, 0
	s_add_u32 s52, s28, 0x41000
	s_addc_u32 s53, s29, 0
	s_add_u32 s54, s28, 0x41100
	s_addc_u32 s55, s29, 0
	s_add_u32 s68, s28, 0x41200
	v_readlane_b32 s3, v254, 0
	s_addc_u32 s69, s29, 0
	s_mul_i32 s3, s35, s3
	s_add_u32 s70, s28, 0x41300
	s_mul_i32 s3, s3, s34
	s_addc_u32 s71, s29, 0
	s_mov_b32 s10, 1
	v_mov_b32_e32 v16, 0
	s_branch .LBB0_497

.LBB0_571:
	s_cmp_gt_i32 s31, 5
	s_cselect_b64 s[4:5], -1, 0
	s_and_b64 s[0:1], s[0:1], s[4:5]
	s_andn2_b64 vcc, exec, s[0:1]
	s_cbranch_vccnz .LBB0_625
	s_waitcnt vmcnt(0)
	s_waitcnt vmcnt(0) lgkmcnt(0)
	s_barrier
	s_mov_b64 s[0:1], exec
	v_readlane_b32 s6, v254, 1
	v_readlane_b32 s7, v254, 2
	s_and_b64 s[6:7], s[0:1], s[6:7]
	s_mov_b64 exec, s[6:7]
	s_cbranch_execz .LBB0_624
	buffer_wbl2 sc1
	s_add_i32 s3, 0, 0x23ff0
	v_mov_b32_e32 v0, s3
	s_waitcnt vmcnt(0) expcnt(0) lgkmcnt(0)
	ds_read_b32 v2, v0
	s_add_i32 s3, 0, 0x23ff4
	v_mov_b32_e32 v0, s3
	ds_read_b32 v0, v0
	s_waitcnt lgkmcnt(1)
	v_cmp_ne_u32_e32 vcc, 0, v2
	s_cbranch_vccnz .LBB0_588
	s_add_u32 s6, s28, 0x40200
	s_addc_u32 s7, s29, 0
	s_add_u32 s8, s28, 0x40400
	s_addc_u32 s9, s29, 0
	s_add_u32 s12, s28, 0x40500
	s_addc_u32 s13, s29, 0
	s_add_u32 s14, s28, 0x40600
	s_addc_u32 s15, s29, 0
	s_add_u32 s16, s28, 0x40700
	s_addc_u32 s17, s29, 0
	s_add_u32 s18, s28, 0x40800
	s_addc_u32 s19, s29, 0
	s_add_u32 s36, s28, 0x40900
	s_addc_u32 s37, s29, 0
	s_add_u32 s38, s28, 0x40a00
	s_addc_u32 s39, s29, 0
	s_add_u32 s40, s28, 0x40b00
	s_addc_u32 s41, s29, 0
	s_add_u32 s42, s28, 0x40c00
	s_addc_u32 s43, s29, 0
	s_add_u32 s44, s28, 0x40d00
	s_addc_u32 s45, s29, 0
	s_add_u32 s46, s28, 0x40e00
	s_addc_u32 s47, s29, 0
	s_add_u32 s48, s28, 0x40f00
	s_addc_u32 s49, s29, 0
	s_add_u32 s50, s28, 0x41000
	s_addc_u32 s51, s29, 0
	s_add_u32 s52, s28, 0x41100
	s_addc_u32 s53, s29, 0
	s_add_u32 s54, s28, 0x41200
	v_readlane_b32 s3, v254, 0
	s_addc_u32 s55, s29, 0
	s_mul_i32 s3, s35, s3
	s_add_u32 s66, s28, 0x41300
	s_mul_i32 s3, s3, s34
	s_addc_u32 s67, s29, 0
	s_mov_b32 s10, 1
	v_mov_b32_e32 v16, 0
	s_branch .LBB0_576

.LBB0_629:
	s_cmp_gt_i32 s31, 6
	s_cselect_b64 s[0:1], -1, 0
	s_and_b64 s[4:5], s[4:5], s[0:1]
	s_andn2_b64 vcc, exec, s[4:5]
	s_cbranch_vccnz .LBB0_683
	s_waitcnt vmcnt(0)
	s_waitcnt vmcnt(0) lgkmcnt(0)
	s_barrier
	s_mov_b64 s[4:5], exec
	v_readlane_b32 s6, v254, 1
	v_readlane_b32 s7, v254, 2
	s_and_b64 s[6:7], s[4:5], s[6:7]
	s_mov_b64 exec, s[6:7]
	s_cbranch_execz .LBB0_682
	buffer_wbl2 sc1
	s_add_i32 s3, 0, 0x23ff0
	v_mov_b32_e32 v0, s3
	s_waitcnt vmcnt(0) expcnt(0) lgkmcnt(0)
	ds_read_b32 v2, v0
	s_add_i32 s3, 0, 0x23ff4
	v_mov_b32_e32 v0, s3
	ds_read_b32 v0, v0
	s_waitcnt lgkmcnt(1)
	v_cmp_ne_u32_e32 vcc, 0, v2
	s_cbranch_vccnz .LBB0_646
	s_add_u32 s6, s28, 0x40200
	s_addc_u32 s7, s29, 0
	s_add_u32 s8, s28, 0x40400
	s_addc_u32 s9, s29, 0
	s_add_u32 s12, s28, 0x40500
	s_addc_u32 s13, s29, 0
	s_add_u32 s14, s28, 0x40600
	s_addc_u32 s15, s29, 0
	s_add_u32 s16, s28, 0x40700
	s_addc_u32 s17, s29, 0
	s_add_u32 s18, s28, 0x40800
	s_addc_u32 s19, s29, 0
	s_add_u32 s24, s28, 0x40900
	s_addc_u32 s25, s29, 0
	s_add_u32 s36, s28, 0x40a00
	s_addc_u32 s37, s29, 0
	s_add_u32 s38, s28, 0x40b00
	s_addc_u32 s39, s29, 0
	s_add_u32 s40, s28, 0x40c00
	s_addc_u32 s41, s29, 0
	s_add_u32 s42, s28, 0x40d00
	s_addc_u32 s43, s29, 0
	s_add_u32 s44, s28, 0x40e00
	s_addc_u32 s45, s29, 0
	s_add_u32 s46, s28, 0x40f00
	s_addc_u32 s47, s29, 0
	s_add_u32 s48, s28, 0x41000
	s_addc_u32 s49, s29, 0
	s_add_u32 s50, s28, 0x41100
	s_addc_u32 s51, s29, 0
	s_add_u32 s52, s28, 0x41200
	v_readlane_b32 s3, v254, 0
	s_addc_u32 s53, s29, 0
	s_mul_i32 s3, s35, s3
	s_add_u32 s54, s28, 0x41300
	s_mul_i32 s3, s3, s34
	s_addc_u32 s55, s29, 0
	s_mov_b32 s10, 1
	v_mov_b32_e32 v16, 0
	s_branch .LBB0_634

.LBB0_700:
	s_cmp_gt_i32 s31, 7
	s_cselect_b64 s[4:5], -1, 0
	s_and_b64 s[0:1], s[0:1], s[4:5]
	s_andn2_b64 vcc, exec, s[0:1]
	s_cbranch_vccnz .LBB0_754
	s_waitcnt vmcnt(0)
	s_waitcnt vmcnt(0) lgkmcnt(0)
	s_barrier
	s_mov_b64 s[0:1], exec
	v_readlane_b32 s6, v254, 1
	v_readlane_b32 s7, v254, 2
	s_and_b64 s[6:7], s[0:1], s[6:7]
	s_mov_b64 exec, s[6:7]
	s_cbranch_execz .LBB0_753
	buffer_wbl2 sc1
	s_add_i32 s3, 0, 0x23ff0
	v_mov_b32_e32 v0, s3
	s_waitcnt vmcnt(0) expcnt(0) lgkmcnt(0)
	ds_read_b32 v2, v0
	s_add_i32 s3, 0, 0x23ff4
	v_mov_b32_e32 v0, s3
	ds_read_b32 v0, v0
	s_waitcnt lgkmcnt(1)
	v_cmp_ne_u32_e32 vcc, 0, v2
	s_cbranch_vccnz .LBB0_717
	s_add_u32 s6, s28, 0x40200
	s_addc_u32 s7, s29, 0
	s_add_u32 s8, s28, 0x40400
	s_addc_u32 s9, s29, 0
	s_add_u32 s12, s28, 0x40500
	s_addc_u32 s13, s29, 0
	s_add_u32 s14, s28, 0x40600
	s_addc_u32 s15, s29, 0
	s_add_u32 s16, s28, 0x40700
	s_addc_u32 s17, s29, 0
	s_add_u32 s18, s28, 0x40800
	s_addc_u32 s19, s29, 0
	s_add_u32 s22, s28, 0x40900
	s_addc_u32 s23, s29, 0
	s_add_u32 s24, s28, 0x40a00
	s_addc_u32 s25, s29, 0
	s_add_u32 s36, s28, 0x40b00
	s_addc_u32 s37, s29, 0
	s_add_u32 s38, s28, 0x40c00
	s_addc_u32 s39, s29, 0
	s_add_u32 s40, s28, 0x40d00
	s_addc_u32 s41, s29, 0
	s_add_u32 s42, s28, 0x40e00
	s_addc_u32 s43, s29, 0
	s_add_u32 s44, s28, 0x40f00
	s_addc_u32 s45, s29, 0
	s_add_u32 s46, s28, 0x41000
	s_addc_u32 s47, s29, 0
	s_add_u32 s48, s28, 0x41100
	s_addc_u32 s49, s29, 0
	s_add_u32 s50, s28, 0x41200
	v_readlane_b32 s3, v254, 0
	s_addc_u32 s51, s29, 0
	s_mul_i32 s3, s35, s3
	s_add_u32 s52, s28, 0x41300
	s_mul_i32 s3, s3, s34
	s_addc_u32 s53, s29, 0
	s_mov_b32 s10, 1
	v_mov_b32_e32 v16, 0
	s_branch .LBB0_705

.LBB0_783:
	s_cmp_gt_i32 s31, 8
	s_cselect_b64 s[0:1], -1, 0
	s_and_b64 s[4:5], s[6:7], s[0:1]
	s_andn2_b64 vcc, exec, s[4:5]
	s_cbranch_vccnz .LBB0_837
	s_waitcnt vmcnt(0)
	s_waitcnt vmcnt(0) lgkmcnt(0)
	s_barrier
	s_mov_b64 s[4:5], exec
	v_readlane_b32 s6, v254, 1
	v_readlane_b32 s7, v254, 2
	s_and_b64 s[6:7], s[4:5], s[6:7]
	s_mov_b64 exec, s[6:7]
	s_cbranch_execz .LBB0_836
	buffer_wbl2 sc1
	s_add_i32 s3, 0, 0x23ff0
	v_mov_b32_e32 v0, s3
	s_waitcnt vmcnt(0) expcnt(0) lgkmcnt(0)
	ds_read_b32 v2, v0
	s_add_i32 s3, 0, 0x23ff4
	v_mov_b32_e32 v0, s3
	ds_read_b32 v0, v0
	s_waitcnt lgkmcnt(1)
	v_cmp_ne_u32_e32 vcc, 0, v2
	s_cbranch_vccnz .LBB0_800
	s_add_u32 s6, s28, 0x40200
	s_addc_u32 s7, s29, 0
	s_add_u32 s8, s28, 0x40400
	s_addc_u32 s9, s29, 0
	s_add_u32 s10, s28, 0x40500
	s_addc_u32 s11, s29, 0
	s_add_u32 s12, s28, 0x40600
	s_addc_u32 s13, s29, 0
	s_add_u32 s14, s28, 0x40700
	s_addc_u32 s15, s29, 0
	s_add_u32 s16, s28, 0x40800
	s_addc_u32 s17, s29, 0
	s_add_u32 s18, s28, 0x40900
	s_addc_u32 s19, s29, 0
	s_add_u32 s20, s28, 0x40a00
	s_addc_u32 s21, s29, 0
	s_add_u32 s22, s28, 0x40b00
	s_addc_u32 s23, s29, 0
	s_add_u32 s24, s28, 0x40c00
	s_addc_u32 s25, s29, 0
	s_add_u32 s26, s28, 0x40d00
	s_addc_u32 s27, s29, 0
	s_add_u32 s36, s28, 0x40e00
	s_addc_u32 s37, s29, 0
	s_add_u32 s38, s28, 0x40f00
	s_addc_u32 s39, s29, 0
	s_add_u32 s40, s28, 0x41000
	s_addc_u32 s41, s29, 0
	s_add_u32 s42, s28, 0x41100
	s_addc_u32 s43, s29, 0
	s_add_u32 s44, s28, 0x41200
	v_readlane_b32 s3, v254, 0
	s_addc_u32 s45, s29, 0
	s_mul_i32 s3, s35, s3
	s_add_u32 s46, s28, 0x41300
	s_mul_i32 s3, s3, s34
	s_addc_u32 s47, s29, 0
	s_mov_b32 s31, 1
	v_mov_b32_e32 v16, 0
	s_branch .LBB0_788
